# v38 + s_setprio 1 around the 64-MFMA block of the indexer scoring loop
# speedup vs baseline: 1.0058x; 1.0024x over previous
; DI float relu_i(float x) { return __int_as_float(max(__float_as_int(x), 0)); }
; DI void topk_group(const Params& p, int t, char* smem, unsigned* scr1, unsigned* scr2, unsigned* scr3) {
;     ...
;     for (int kt0 = w; kt0 < ntile; kt0 += 32) {
;       bf16x8 b0[8], b1[8];
; #pragma unroll
;       for (int g = 0; g < 8; ++g) {
;         const int kt = min(kt0 + g * 4, ntile - 1);
;         const u16* kp = ixk + (size_t)(kt * 16 + fr) * 64 + fq * 8;
;         b0[g] = *(const bf16x8*)kp; b1[g] = *(const bf16x8*)(kp + 32);
;       }
;       float pt[NQ][8];
; #pragma unroll
;       for (int g = 0; g < 8; ++g) {
; #pragma unroll
;         for (int qi = 0; qi < NQ; ++qi) {
;           f32x4 c = {0.f, 0.f, 0.f, 0.f};
;           c = __builtin_amdgcn_mfma_f32_16x16x32_bf16(a0[qi], b0[g], c, 0, 0, 0);
;           c = __builtin_amdgcn_mfma_f32_16x16x32_bf16(a1[qi], b1[g], c, 0, 0, 0);
;           pt[qi][g] = relu_i(c[0]) * wv[qi][0] + relu_i(c[1]) * wv[qi][1] + relu_i(c[2]) * wv[qi][2] + relu_i(c[3]) * wv[qi][3];
;         }
;       }
.LBB0_1362:
	v_min_i32_e32 v48, v216, v212
	v_lshl_or_b32 v48, v48, 4, v187
	v_ashrrev_i32_e32 v49, 31, v48
	v_lshlrev_b64 v[48:49], 7, v[48:49]
	v_lshl_add_u64 v[48:49], v[190:191], 0, v[48:49]
	global_load_dwordx4 v[104:107], v[48:49], off
	global_load_dwordx4 v[108:111], v[48:49], off offset:64
	v_add_u32_e32 v48, 4, v216
	v_min_i32_e32 v48, v48, v212
	v_lshl_or_b32 v48, v48, 4, v187
	v_ashrrev_i32_e32 v49, 31, v48
	v_lshlrev_b64 v[48:49], 7, v[48:49]
	v_lshl_add_u64 v[48:49], v[190:191], 0, v[48:49]
	global_load_dwordx4 v[96:99], v[48:49], off
	global_load_dwordx4 v[100:103], v[48:49], off offset:64
	v_add_u32_e32 v48, 8, v216
	v_min_i32_e32 v48, v48, v212
	v_lshl_or_b32 v48, v48, 4, v187
	v_ashrrev_i32_e32 v49, 31, v48
	v_lshlrev_b64 v[48:49], 7, v[48:49]
	v_lshl_add_u64 v[48:49], v[190:191], 0, v[48:49]
	global_load_dwordx4 v[92:95], v[48:49], off
	global_load_dwordx4 v[88:91], v[48:49], off offset:64
	v_add_u32_e32 v48, 12, v216
	v_min_i32_e32 v48, v48, v212
	v_lshl_or_b32 v48, v48, 4, v187
	v_ashrrev_i32_e32 v49, 31, v48
	v_lshlrev_b64 v[48:49], 7, v[48:49]
	v_lshl_add_u64 v[48:49], v[190:191], 0, v[48:49]
	global_load_dwordx4 v[84:87], v[48:49], off
	global_load_dwordx4 v[80:83], v[48:49], off offset:64
	v_add_u32_e32 v48, 16, v216
	v_min_i32_e32 v48, v48, v212
	v_lshl_or_b32 v48, v48, 4, v187
	v_ashrrev_i32_e32 v49, 31, v48
	v_lshlrev_b64 v[48:49], 7, v[48:49]
	v_lshl_add_u64 v[48:49], v[190:191], 0, v[48:49]
	global_load_dwordx4 v[76:79], v[48:49], off
	global_load_dwordx4 v[68:71], v[48:49], off offset:64
	v_add_u32_e32 v48, 20, v216
	v_min_i32_e32 v48, v48, v212
	v_lshl_or_b32 v48, v48, 4, v187
	v_ashrrev_i32_e32 v49, 31, v48
	v_lshlrev_b64 v[48:49], 7, v[48:49]
	v_lshl_add_u64 v[48:49], v[190:191], 0, v[48:49]
	global_load_dwordx4 v[64:67], v[48:49], off
	global_load_dwordx4 v[52:55], v[48:49], off offset:64
	v_add_u32_e32 v48, 24, v216
	v_min_i32_e32 v48, v48, v212
	v_lshl_or_b32 v48, v48, 4, v187
	v_ashrrev_i32_e32 v49, 31, v48
	v_lshlrev_b64 v[48:49], 7, v[48:49]
	v_lshl_add_u64 v[48:49], v[190:191], 0, v[48:49]
	global_load_dwordx4 v[72:75], v[48:49], off
	s_nop 0
	global_load_dwordx4 v[48:51], v[48:49], off offset:64
	v_add_u32_e32 v56, 28, v216
	v_min_i32_e32 v56, v56, v212
	v_lshl_or_b32 v56, v56, 4, v187
	v_ashrrev_i32_e32 v57, 31, v56
	v_lshlrev_b64 v[56:57], 7, v[56:57]
	v_lshl_add_u64 v[60:61], v[190:191], 0, v[56:57]
	global_load_dwordx4 v[56:59], v[60:61], off
	s_nop 0
	global_load_dwordx4 v[60:63], v[60:61], off offset:64
	s_waitcnt vmcnt(15)
	s_setprio 1
	v_mfma_f32_16x16x32_bf16 v[112:115], v[0:3], v[104:107], 0
	s_waitcnt vmcnt(14)
	v_mfma_f32_16x16x32_bf16 v[112:115], v[4:7], v[108:111], v[112:115]
	s_nop 7
	v_max_i32_e32 v113, 0, v113
	v_max_i32_e32 v112, 0, v112
	v_mul_f32_e32 v184, v17, v113
	v_fmac_f32_e32 v184, v16, v112
	v_max_i32_e32 v112, 0, v114
	v_fmac_f32_e32 v184, v18, v112
	v_max_i32_e32 v112, 0, v115
	v_fmac_f32_e32 v184, v19, v112
	v_mfma_f32_16x16x32_bf16 v[112:115], v[8:11], v[104:107], 0
	v_mfma_f32_16x16x32_bf16 v[140:143], v[12:15], v[108:111], v[112:115]
	v_mfma_f32_16x16x32_bf16 v[112:115], v[24:27], v[104:107], 0
	v_mfma_f32_16x16x32_bf16 v[104:107], v[32:35], v[104:107], 0
	v_mfma_f32_16x16x32_bf16 v[124:127], v[28:31], v[108:111], v[112:115]
	v_mfma_f32_16x16x32_bf16 v[108:111], v[36:39], v[108:111], v[104:107]
	s_waitcnt vmcnt(13)
	v_mfma_f32_16x16x32_bf16 v[104:107], v[0:3], v[96:99], 0
	s_waitcnt vmcnt(12)
	v_mfma_f32_16x16x32_bf16 v[104:107], v[4:7], v[100:103], v[104:107]
	s_nop 7
	v_max_i32_e32 v105, 0, v105
	v_max_i32_e32 v104, 0, v104
	v_mul_f32_e32 v193, v17, v105
	v_fmac_f32_e32 v193, v16, v104
	v_max_i32_e32 v104, 0, v106
	v_fmac_f32_e32 v193, v18, v104
	v_max_i32_e32 v104, 0, v107
	v_fmac_f32_e32 v193, v19, v104
	v_mfma_f32_16x16x32_bf16 v[104:107], v[8:11], v[96:99], 0
	s_nop 0
	v_permlane32_swap_b32_e32 v184, v193
	v_mfma_f32_16x16x32_bf16 v[168:171], v[12:15], v[100:103], v[104:107]
	v_mfma_f32_16x16x32_bf16 v[104:107], v[24:27], v[96:99], 0
	v_mfma_f32_16x16x32_bf16 v[96:99], v[32:35], v[96:99], 0
	v_mfma_f32_16x16x32_bf16 v[152:155], v[36:39], v[100:103], v[96:99]
	s_waitcnt vmcnt(11)
; DI float relu_i(float x) { return __int_as_float(max(__float_as_int(x), 0)); }
; DI unsigned fkey(float f) { unsigned u = __float_as_uint(f); return (u & 0x80000000u) ? ~u : (u | 0x80000000u); }
; DI void topk_group(const Params& p, int t, char* smem, unsigned* scr1, unsigned* scr2, unsigned* scr3) {
;     ...
; #pragma unroll
;       for (int g = 0; g < 8; ++g) {
; #pragma unroll
;         for (int qi = 0; qi < NQ; ++qi) {
;           f32x4 c = {0.f, 0.f, 0.f, 0.f};
;           c = __builtin_amdgcn_mfma_f32_16x16x32_bf16(a0[qi], b0[g], c, 0, 0, 0);
;           c = __builtin_amdgcn_mfma_f32_16x16x32_bf16(a1[qi], b1[g], c, 0, 0, 0);
;           pt[qi][g] = relu_i(c[0]) * wv[qi][0] + relu_i(c[1]) * wv[qi][1] + relu_i(c[2]) * wv[qi][2] + relu_i(c[3]) * wv[qi][3];
;         }
;       }
; #pragma unroll
;       for (int g = 0; g < 8; g += 2) {
;         const int kt = kt0 + (g + (lane >> 5)) * 4;
;         const bool st = (lane & 16) == 0 && kt < ntile;
; #pragma unroll
;         for (int qi = 0; qi < NQ; ++qi) {
;           auto r32 = __builtin_amdgcn_permlane32_swap(__float_as_uint(pt[qi][g]), __float_as_uint(pt[qi][g + 1]), false, false);
;           float s2 = __uint_as_float(r32[0]) + __uint_as_float(r32[1]);
;           auto r16 = __builtin_amdgcn_permlane16_swap(__float_as_uint(s2), __float_as_uint(s2), false, false);
;           float sv = __uint_as_float(r16[0]) + __uint_as_float(r16[1]);
;           if (st) {
;             unsigned u = fkey(sv);
;             if (qi == 0) { sc[kt * 16 + fr] = u; atomicAdd(&hist[u >> 21], 1); }
;             else if (qi == 1) scr1[kt * 16 + fr] = u;
;             else if (qi == 2) scr2[kt * 16 + fr] = u;
;             else scr3[kt * 16 + fr] = u;
	v_mfma_f32_16x16x32_bf16 v[96:99], v[0:3], v[92:95], 0
	s_waitcnt vmcnt(10)
	v_mfma_f32_16x16x32_bf16 v[148:151], v[4:7], v[88:91], v[96:99]
	v_mfma_f32_16x16x32_bf16 v[96:99], v[8:11], v[92:95], 0
	v_mfma_f32_16x16x32_bf16 v[120:123], v[12:15], v[88:91], v[96:99]
	v_mfma_f32_16x16x32_bf16 v[96:99], v[24:27], v[92:95], 0
	v_mfma_f32_16x16x32_bf16 v[92:95], v[32:35], v[92:95], 0
	v_mfma_f32_16x16x32_bf16 v[128:131], v[28:31], v[88:91], v[96:99]
	v_mfma_f32_16x16x32_bf16 v[112:115], v[36:39], v[88:91], v[92:95]
	s_waitcnt vmcnt(9)
	v_mfma_f32_16x16x32_bf16 v[88:91], v[0:3], v[84:87], 0
	s_waitcnt vmcnt(8)
	v_mfma_f32_16x16x32_bf16 v[164:167], v[4:7], v[80:83], v[88:91]
	v_mfma_f32_16x16x32_bf16 v[88:91], v[8:11], v[84:87], 0
	v_mfma_f32_16x16x32_bf16 v[156:159], v[12:15], v[80:83], v[88:91]
	v_mfma_f32_16x16x32_bf16 v[88:91], v[24:27], v[84:87], 0
	v_mfma_f32_16x16x32_bf16 v[84:87], v[32:35], v[84:87], 0
	v_mfma_f32_16x16x32_bf16 v[144:147], v[28:31], v[80:83], v[88:91]
	v_mfma_f32_16x16x32_bf16 v[132:135], v[36:39], v[80:83], v[84:87]
	s_waitcnt vmcnt(7)
	v_mfma_f32_16x16x32_bf16 v[80:83], v[0:3], v[76:79], 0
	s_waitcnt vmcnt(6)
	v_mfma_f32_16x16x32_bf16 v[116:119], v[4:7], v[68:71], v[80:83]
	v_mfma_f32_16x16x32_bf16 v[80:83], v[8:11], v[76:79], 0
	v_mfma_f32_16x16x32_bf16 v[96:99], v[12:15], v[68:71], v[80:83]
	v_mfma_f32_16x16x32_bf16 v[80:83], v[24:27], v[76:79], 0
	v_mfma_f32_16x16x32_bf16 v[76:79], v[32:35], v[76:79], 0
	v_mfma_f32_16x16x32_bf16 v[80:83], v[28:31], v[68:71], v[80:83]
	v_mfma_f32_16x16x32_bf16 v[68:71], v[36:39], v[68:71], v[76:79]
	s_waitcnt vmcnt(5)
	v_mfma_f32_16x16x32_bf16 v[76:79], v[0:3], v[64:67], 0
	s_waitcnt vmcnt(4)
	v_mfma_f32_16x16x32_bf16 v[136:139], v[4:7], v[52:55], v[76:79]
	v_mfma_f32_16x16x32_bf16 v[76:79], v[8:11], v[64:67], 0
	v_mfma_f32_16x16x32_bf16 v[160:163], v[28:31], v[100:103], v[104:107]
	v_mfma_f32_16x16x32_bf16 v[104:107], v[12:15], v[52:55], v[76:79]
	v_mfma_f32_16x16x32_bf16 v[76:79], v[24:27], v[64:67], 0
	v_mfma_f32_16x16x32_bf16 v[64:67], v[32:35], v[64:67], 0
	v_mfma_f32_16x16x32_bf16 v[92:95], v[28:31], v[52:55], v[76:79]
	v_mfma_f32_16x16x32_bf16 v[84:87], v[36:39], v[52:55], v[64:67]
	s_waitcnt vmcnt(3)
	v_mfma_f32_16x16x32_bf16 v[52:55], v[0:3], v[72:75], 0
	s_waitcnt vmcnt(2)
	v_mfma_f32_16x16x32_bf16 v[76:79], v[4:7], v[48:51], v[52:55]
	v_mfma_f32_16x16x32_bf16 v[52:55], v[8:11], v[72:75], 0
	v_mfma_f32_16x16x32_bf16 v[64:67], v[12:15], v[48:51], v[52:55]
	v_mfma_f32_16x16x32_bf16 v[52:55], v[24:27], v[72:75], 0
	v_mfma_f32_16x16x32_bf16 v[72:75], v[32:35], v[72:75], 0
	v_mfma_f32_16x16x32_bf16 v[52:55], v[28:31], v[48:51], v[52:55]
	v_mfma_f32_16x16x32_bf16 v[48:51], v[36:39], v[48:51], v[72:75]
	s_waitcnt vmcnt(1)
	v_mfma_f32_16x16x32_bf16 v[72:75], v[0:3], v[56:59], 0
	s_waitcnt vmcnt(0)
	v_mfma_f32_16x16x32_bf16 v[100:103], v[4:7], v[60:63], v[72:75]
	v_mfma_f32_16x16x32_bf16 v[72:75], v[8:11], v[56:59], 0
	v_mfma_f32_16x16x32_bf16 v[88:91], v[12:15], v[60:63], v[72:75]
	v_mfma_f32_16x16x32_bf16 v[72:75], v[24:27], v[56:59], 0
	v_mfma_f32_16x16x32_bf16 v[56:59], v[32:35], v[56:59], 0
	v_mfma_f32_16x16x32_bf16 v[72:75], v[28:31], v[60:63], v[72:75]
	v_mfma_f32_16x16x32_bf16 v[56:59], v[36:39], v[60:63], v[56:59]
	s_setprio 0
	v_add_u32_e32 v61, v213, v216
	v_add_f32_e32 v62, v184, v193
	v_cmp_lt_u32_e64 s[2:3], v61, v211
	v_mov_b32_e32 v63, v62
	s_and_b64 s[0:1], vcc, s[2:3]
	s_nop 0
	v_permlane16_swap_b32_e32 v62, v63
	v_add_u32_e32 v60, v215, v214
	s_and_saveexec_b64 s[6:7], s[0:1]
	s_cbranch_execz .LBB0_1364
	v_add_f32_e32 v62, v62, v63
	v_not_b32_e32 v63, v62
	v_or_b32_e32 v184, 0x80000000, v62
	v_cmp_gt_i32_e64 s[2:3], 0, v62
	s_nop 1
	v_cndmask_b32_e64 v62, v184, v63, s[2:3]
	ds_write_b32 v60, v62
	v_lshrrev_b32_e32 v62, 19, v62
	v_and_b32_e32 v62, 0x1ffc, v62
	v_add_u32_e32 v62, v197, v62
	ds_add_u32 v62, v202
